# NA softmax exponent folded to one fma per element ((x-m)*log2e -> fma(x,log2e,-m*log2e)), on top of LDS read hoisting etc.
# baseline (speedup 1.0000x reference)
; template <bool UPFRONT, class KP, class VP, class MOD>
; __device__ __forceinline__ void attn16(const bf16x8 (&qf)[2], KP kptr, VP vptr, MOD mod, bf16_t* outp  , int fr, int fq) {
;     bf16x8 kf[16][2];
; #pragma unroll
;     for (int t = 0; t < 16; ++t) if (UPFRONT) { const int key = 32 * (t >> 1) + 8 * (fr >> 2) + 4 * (t & 1) + (fr & 3); kf[t][0] = kptr(key, 0); kf[t][1] = kptr(key, 1); }
;     f32x4 st[16];
;     float mx = -3.0e38f;
; #pragma unroll
;     for (int t = 0; t < 16; ++t) {
;         f32x4 acc = (f32x4){0.f, 0.f, 0.f, 0.f};
;         if (!UPFRONT) { const int key = 32 * (t >> 1) + 8 * (fr >> 2) + 4 * (t & 1) + (fr & 3); kf[t][0] = kptr(key, 0); kf[t][1] = kptr(key, 1); }
;         acc = __builtin_amdgcn_mfma_f32_16x16x32_bf16(kf[t][0], qf[0], acc, 0, 0, 0);
;         acc = __builtin_amdgcn_mfma_f32_16x16x32_bf16(kf[t][1], qf[1], acc, 0, 0, 0);
; #pragma unroll
;         for (int r = 0; r < 4; ++r) { const float v = mod(acc[r], t >> 1, t & 1, r); acc[r] = v; mx = fmaxf(mx, v); }
;         st[t] = acc;
;     }
; __device__ __forceinline__ void na_phase(const bf16_t* proj, const bf16_t* vT, const float* rpb, bf16_t* mix, unsigned char* lds, int tid, int bx) {
;     ...
;             int fqx = fq; asm volatile("" : "+v"(fqx));
;             int sl[8];
; #pragma unroll
;             for (int q = 0; q < 8; ++q) sl[q] = (rs + q) % 9;
;             bf16x8 qf[2]; qf[0] = qfe[0]; qf[1] = qfe[1];
;             const float* rp = lrp + (rs - r + 7) * 31;
;             const int gk = ((fr >> 1) & 1) | ((((kstart >> 3) + (fr >> 2)) & 3) << 1);
;             const unsigned char* kimg = lds + (kstart + 8 * (fr >> 2) + (fr & 3)) * 128;
;             const unsigned char* vimg = lds + NA_VOFF + ((kstart >> 3) + fqx) * 16;
;             attn16<false>(qf,
;                    [&](int key, int ks) { return *(const bf16x8*)(kimg + sl[key >> 5] * 8192 + ((key >> 2) & 1) * 512 + (((4 * ks + fqx) ^ gk) << 4)); },
;                    [&](int d, int s) { return *(const bf16x8*)(vimg + d * NA_VP + sl[s] * 128); },
;                    [&](float v, int s, int pp, int rr) { const int ix = pp * 4 + rr; const unsigned dc = (ix & 1) ? (dcp[ix >> 1] >> 16) : (dcp[ix >> 1] & 0xffffu); return v * 0.125f + rp[s * 31 + dc]; },
.LBB0_168:
	s_cmp_gt_i32 s1, 3
	s_cselect_b32 s0, s6, 0
	s_mul_i32 s1, s0, 57
	s_lshr_b32 s6, s1, 9
	s_mul_i32 s6, s6, 9
	s_sub_i32 s6, s0, s6
	s_and_b32 s34, s6, 0xff
	s_add_i32 s6, s1, 57
	s_bfe_u32 s6, s6, 0x40009
	s_mul_i32 s6, s6, 9
	s_sub_i32 s6, s0, s6
	s_add_i32 s6, s6, 1
	s_and_b32 s31, s6, 0xff
	s_add_i32 s6, s1, 0x72
	s_bfe_u32 s6, s6, 0x40009
	s_mul_i32 s6, s6, 9
	s_sub_i32 s6, s0, s6
	s_add_i32 s6, s6, 2
	s_and_b32 s30, s6, 0xff
	s_add_i32 s6, s1, 0xab
	s_bfe_u32 s6, s6, 0x40009
	s_mul_i32 s6, s6, 9
	v_mov_b32_e32 v102, v184
	s_sub_i32 s6, s0, s6
	v_ashrrev_i32_e32 v99, 31, v98
	s_waitcnt lgkmcnt(0)
	s_barrier
	s_add_i32 s6, s6, 3
	v_add_u32_e32 v100, v102, v187
	s_and_b32 s29, s6, 0xff
	s_add_i32 s6, s1, 0xe4
	v_lshl_add_u32 v210, v100, 4, s73
	v_lshlrev_b64 v[100:101], 11, v[98:99]
	v_xor_b32_e32 v99, v102, v188
	s_bfe_u32 s6, s6, 0x40009
	v_lshlrev_b32_e32 v213, 4, v99
	v_add_u32_e32 v99, 4, v102
	s_mul_i32 s6, s6, 9
	v_xor_b32_e32 v99, v99, v188
	s_sub_i32 s6, s0, s6
	v_lshlrev_b32_e32 v211, 4, v99
	v_lshl_add_u32 v99, s34, 13, v189
	s_add_i32 s6, s6, 4
	v_add_u32_e32 v114, v99, v213
	ds_read_b128 v[236:239], v114
	s_and_b32 s28, s6, 0xff
	s_add_i32 s6, s1, 0x11d
	s_bfe_u32 s6, s6, 0x40009
	s_mul_i32 s6, s6, 9
	s_sub_i32 s6, s0, s6
	v_add_u32_e32 v115, v99, v211
	ds_read_b128 v[240:243], v115
	s_add_i32 s6, s6, 5
	s_and_b32 s15, s6, 0xff
	s_add_i32 s6, s1, 0x156
	s_addk_i32 s1, 0x18f
	s_bfe_u32 s6, s6, 0x40009
	s_bfe_u32 s1, s1, 0x40009
	s_mul_i32 s6, s6, 9
	s_mul_i32 s1, s1, 9
	s_sub_i32 s6, s0, s6
	s_sub_i32 s1, s0, s1
	s_add_i32 s0, s0, s52
	s_mulk_i32 s0, 0x7c
	s_waitcnt vmcnt(1)
	s_waitcnt lgkmcnt(1)
	v_mfma_f32_16x16x32_bf16 v[102:105], v[236:239], v[76:79], 0
	ds_read_b128 v[236:239], v114 offset:512
	s_add_i32 s0, s0, 0
	s_add_i32 s0, s0, 0x24800
	v_lshl_add_u32 v130, v191, 2, s0
	v_lshl_add_u32 v131, v192, 2, s0
	s_waitcnt vmcnt(0)
	s_waitcnt lgkmcnt(1)
	v_mfma_f32_16x16x32_bf16 v[110:113], v[240:243], v[72:75], v[102:105]
	ds_read_b128 v[240:243], v115 offset:512
	ds_read2_b32 v[108:109], v130 offset0:217 offset1:248
	ds_read2_b32 v[106:107], v131 offset0:217 offset1:248
	v_lshl_add_u32 v132, v193, 2, s0
	v_lshl_add_u32 v133, v194, 2, s0
	ds_read2_b32 v[104:105], v132 offset0:217 offset1:248
	ds_read2_b32 v[102:103], v133 offset0:217 offset1:248
	s_nop 0
	s_waitcnt lgkmcnt(3)
	v_fmamk_f32 v108, v110, 0x3e000000, v108
	s_waitcnt lgkmcnt(2)
	v_fmamk_f32 v106, v111, 0x3e000000, v106
	v_max3_f32 v110, v108, s62, v106
	s_waitcnt lgkmcnt(1)
	v_fmamk_f32 v104, v112, 0x3e000000, v104
	s_waitcnt lgkmcnt(0)
	v_fmamk_f32 v99, v113, 0x3e000000, v102
	v_max3_f32 v102, v110, v104, v99
	v_mfma_f32_16x16x32_bf16 v[110:113], v[236:239], v[76:79], 0
	v_lshl_add_u32 v136, v195, 2, s0
	v_lshl_add_u32 v137, v196, 2, s0
	v_lshl_add_u32 v138, v197, 2, s0
	v_mfma_f32_16x16x32_bf16 v[116:119], v[240:243], v[72:75], v[110:113]
	ds_read2_b32 v[114:115], v136 offset0:217 offset1:248
	v_lshl_add_u32 v139, v198, 2, s0
	v_add_u32_e32 v150, 0x400, v130
	ds_read2_b32 v[112:113], v137 offset0:217 offset1:248
	ds_read2_b32 v[110:111], v139 offset0:217 offset1:248
	s_nop 1
	s_waitcnt lgkmcnt(2)
	v_fmamk_f32 v212, v116, 0x3e000000, v114
	v_add_u32_e32 v151, 0x400, v131
	v_add_u32_e32 v152, 0x400, v132
	s_waitcnt lgkmcnt(1)
	v_fmamk_f32 v112, v117, 0x3e000000, v112
	ds_read2_b32 v[116:117], v138 offset0:217 offset1:248
	v_max3_f32 v120, v102, v212, v112
	s_waitcnt lgkmcnt(1)
	v_fmamk_f32 v102, v119, 0x3e000000, v110
	v_add_u32_e32 v164, 0x400, v133
	v_add_u32_e32 v165, 0x400, v136
	s_waitcnt lgkmcnt(0)
	v_fmamk_f32 v114, v118, 0x3e000000, v116
	v_lshl_add_u32 v116, s31, 13, v189
	v_add_u32_e32 v126, v116, v213
	ds_read_b128 v[236:239], v126
	v_max3_f32 v110, v120, v114, v102
	v_add_u32_e32 v116, v116, v211
	ds_read_b128 v[240:243], v116
	s_waitcnt lgkmcnt(1)
	v_mfma_f32_16x16x32_bf16 v[118:121], v[236:239], v[76:79], 0
	ds_read_b128 v[236:239], v126 offset:512
	v_add_u32_e32 v166, 0x400, v137
	v_add_u32_e32 v167, 0x400, v138
	v_add_u32_e32 v214, 0x400, v139
	s_waitcnt lgkmcnt(1)
	v_mfma_f32_16x16x32_bf16 v[118:121], v[240:243], v[72:75], v[118:121]
	ds_read_b128 v[240:243], v116 offset:512
	s_add_i32 s6, s6, 6
	s_and_b32 s14, s6, 0xff
	s_add_i32 s1, s1, 7
	s_and_b32 s6, s1, 0xff
	s_nop 3
	v_fmac_f32_e32 v109, 0x3e000000, v118
	v_fmac_f32_e32 v107, 0x3e000000, v119
	v_fmac_f32_e32 v105, 0x3e000000, v120
	v_fmac_f32_e32 v103, 0x3e000000, v121
	s_waitcnt lgkmcnt(1)
	v_mfma_f32_16x16x32_bf16 v[118:121], v[236:239], v[76:79], 0
	v_lshl_add_u32 v116, s30, 13, v189
	v_add_u32_e32 v134, v116, v213
	v_add_u32_e32 v135, v116, v211
	ds_read_b128 v[236:239], v135
	s_waitcnt lgkmcnt(1)
	v_mfma_f32_16x16x32_bf16 v[118:121], v[240:243], v[72:75], v[118:121]
	ds_read_b128 v[240:243], v134
	v_max3_f32 v110, v110, v109, v107
	v_max3_f32 v110, v110, v105, v103
	s_nop 4
	v_fmac_f32_e32 v115, 0x3e000000, v118
	v_fmac_f32_e32 v113, 0x3e000000, v119
	v_fmac_f32_e32 v117, 0x3e000000, v120
	v_fmac_f32_e32 v111, 0x3e000000, v121
	s_waitcnt lgkmcnt(0)
	v_mfma_f32_16x16x32_bf16 v[118:121], v[240:243], v[76:79], 0
	ds_read_b128 v[240:243], v134 offset:512
	v_max3_f32 v110, v110, v115, v113
	v_max3_f32 v110, v110, v117, v111
	v_mfma_f32_16x16x32_bf16 v[126:129], v[236:239], v[72:75], v[118:121]
	ds_read_b128 v[236:239], v135 offset:512
	ds_read2_b32 v[124:125], v150 offset0:23 offset1:54
	ds_read2_b32 v[122:123], v151 offset0:23 offset1:54
	s_nop 2
	ds_read2_b32 v[120:121], v152 offset0:23 offset1:54
	ds_read2_b32 v[118:119], v164 offset0:23 offset1:54
	s_waitcnt lgkmcnt(3)
	v_fmamk_f32 v124, v126, 0x3e000000, v124
	s_waitcnt lgkmcnt(2)
; template <bool UPFRONT, class KP, class VP, class MOD>
; __device__ __forceinline__ void attn16(const bf16x8 (&qf)[2], KP kptr, VP vptr, MOD mod, bf16_t* outp  , int fr, int fq) {
;     bf16x8 kf[16][2];
; #pragma unroll
;     for (int t = 0; t < 16; ++t) if (UPFRONT) { const int key = 32 * (t >> 1) + 8 * (fr >> 2) + 4 * (t & 1) + (fr & 3); kf[t][0] = kptr(key, 0); kf[t][1] = kptr(key, 1); }
;     f32x4 st[16];
;     float mx = -3.0e38f;
; #pragma unroll
;     for (int t = 0; t < 16; ++t) {
;         f32x4 acc = (f32x4){0.f, 0.f, 0.f, 0.f};
;         if (!UPFRONT) { const int key = 32 * (t >> 1) + 8 * (fr >> 2) + 4 * (t & 1) + (fr & 3); kf[t][0] = kptr(key, 0); kf[t][1] = kptr(key, 1); }
;         acc = __builtin_amdgcn_mfma_f32_16x16x32_bf16(kf[t][0], qf[0], acc, 0, 0, 0);
;         acc = __builtin_amdgcn_mfma_f32_16x16x32_bf16(kf[t][1], qf[1], acc, 0, 0, 0);
; #pragma unroll
;         for (int r = 0; r < 4; ++r) { const float v = mod(acc[r], t >> 1, t & 1, r); acc[r] = v; mx = fmaxf(mx, v); }
;         st[t] = acc;
;     }
; __device__ __forceinline__ void na_phase(const bf16_t* proj, const bf16_t* vT, const float* rpb, bf16_t* mix, unsigned char* lds, int tid, int bx) {
;     ...
;             const float* rp = lrp + (rs - r + 7) * 31;
;             const int gk = ((fr >> 1) & 1) | ((((kstart >> 3) + (fr >> 2)) & 3) << 1);
;             const unsigned char* kimg = lds + (kstart + 8 * (fr >> 2) + (fr & 3)) * 128;
;             const unsigned char* vimg = lds + NA_VOFF + ((kstart >> 3) + fqx) * 16;
;             attn16<false>(qf,
;                    [&](int key, int ks) { return *(const bf16x8*)(kimg + sl[key >> 5] * 8192 + ((key >> 2) & 1) * 512 + (((4 * ks + fqx) ^ gk) << 4)); },
;                    [&](int d, int s) { return *(const bf16x8*)(vimg + d * NA_VP + sl[s] * 128); },
;                    [&](float v, int s, int pp, int rr) { const int ix = pp * 4 + rr; const unsigned dc = (ix & 1) ? (dcp[ix >> 1] >> 16) : (dcp[ix >> 1] & 0xffffu); return v * 0.125f + rp[s * 31 + dc]; },
	v_fmamk_f32 v122, v127, 0x3e000000, v122
	v_max3_f32 v126, v110, v124, v122
	s_waitcnt lgkmcnt(1)
	v_fmamk_f32 v116, v128, 0x3e000000, v120
	s_waitcnt lgkmcnt(0)
	v_fmamk_f32 v110, v129, 0x3e000000, v118
	v_max3_f32 v118, v126, v116, v110
	v_mfma_f32_16x16x32_bf16 v[126:129], v[240:243], v[76:79], 0
	v_mfma_f32_16x16x32_bf16 v[132:135], v[236:239], v[72:75], v[126:129]
	ds_read2_b32 v[130:131], v165 offset0:23 offset1:54
	s_nop 4
	ds_read2_b32 v[128:129], v166 offset0:23 offset1:54
	ds_read2_b32 v[126:127], v214 offset0:23 offset1:54
	s_waitcnt lgkmcnt(2)
	v_fmamk_f32 v120, v132, 0x3e000000, v130
	s_waitcnt lgkmcnt(1)
	v_fmamk_f32 v128, v133, 0x3e000000, v128
	ds_read2_b32 v[132:133], v167 offset0:23 offset1:54
	v_max3_f32 v136, v118, v120, v128
	s_waitcnt lgkmcnt(1)
	v_fmamk_f32 v118, v135, 0x3e000000, v126
	s_waitcnt lgkmcnt(0)
	v_fmamk_f32 v130, v134, 0x3e000000, v132
	v_lshl_add_u32 v132, s29, 13, v189
	v_add_u32_e32 v142, v132, v213
	ds_read_b128 v[240:243], v142
	v_max3_f32 v126, v136, v130, v118
	v_add_u32_e32 v132, v132, v211
	ds_read_b128 v[236:239], v132
	s_waitcnt lgkmcnt(1)
	v_mfma_f32_16x16x32_bf16 v[134:137], v[240:243], v[76:79], 0
	ds_read_b128 v[240:243], v142 offset:512
	s_waitcnt lgkmcnt(1)
	v_mfma_f32_16x16x32_bf16 v[134:137], v[236:239], v[72:75], v[134:137]
	ds_read_b128 v[236:239], v132 offset:512
	s_nop 7
	v_fmac_f32_e32 v125, 0x3e000000, v134
	v_fmac_f32_e32 v123, 0x3e000000, v135
	v_fmac_f32_e32 v121, 0x3e000000, v136
	v_fmac_f32_e32 v119, 0x3e000000, v137
	s_waitcnt lgkmcnt(1)
	v_mfma_f32_16x16x32_bf16 v[134:137], v[240:243], v[76:79], 0
	v_lshl_add_u32 v132, s28, 13, v189
	v_add_u32_e32 v146, v132, v213
	v_add_u32_e32 v147, v132, v211
	ds_read_b128 v[240:243], v147
	s_waitcnt lgkmcnt(1)
	v_mfma_f32_16x16x32_bf16 v[134:137], v[236:239], v[72:75], v[134:137]
	ds_read_b128 v[236:239], v146
	v_max3_f32 v126, v126, v125, v123
	v_max3_f32 v126, v126, v121, v119
	s_nop 4
	v_fmac_f32_e32 v131, 0x3e000000, v134
	v_fmac_f32_e32 v129, 0x3e000000, v135
	v_fmac_f32_e32 v133, 0x3e000000, v136
	v_fmac_f32_e32 v127, 0x3e000000, v137
	s_waitcnt lgkmcnt(0)
	v_mfma_f32_16x16x32_bf16 v[134:137], v[236:239], v[76:79], 0
	ds_read_b128 v[236:239], v146 offset:512
	v_max3_f32 v126, v126, v131, v129
	v_max3_f32 v126, v126, v133, v127
	v_mfma_f32_16x16x32_bf16 v[142:145], v[240:243], v[72:75], v[134:137]
	ds_read_b128 v[240:243], v147 offset:512
	ds_read2_b32 v[140:141], v150 offset0:85 offset1:116
	ds_read2_b32 v[138:139], v151 offset0:85 offset1:116
	s_nop 2
	ds_read2_b32 v[136:137], v152 offset0:85 offset1:116
	ds_read2_b32 v[134:135], v164 offset0:85 offset1:116
	s_waitcnt lgkmcnt(3)
	v_fmamk_f32 v140, v142, 0x3e000000, v140
	s_waitcnt lgkmcnt(2)
	v_fmamk_f32 v138, v143, 0x3e000000, v138
	v_max3_f32 v142, v126, v140, v138
	s_waitcnt lgkmcnt(1)
	v_fmamk_f32 v132, v144, 0x3e000000, v136
	s_waitcnt lgkmcnt(0)
	v_fmamk_f32 v126, v145, 0x3e000000, v134
	v_max3_f32 v134, v142, v132, v126
	v_mfma_f32_16x16x32_bf16 v[142:145], v[236:239], v[76:79], 0
	v_mfma_f32_16x16x32_bf16 v[160:163], v[240:243], v[72:75], v[142:145]
	ds_read2_b32 v[148:149], v165 offset0:85 offset1:116
	ds_read2_b32 v[146:147], v166 offset0:85 offset1:116
	s_nop 3
	ds_read2_b32 v[144:145], v167 offset0:85 offset1:116
	ds_read2_b32 v[142:143], v214 offset0:85 offset1:116
	s_waitcnt lgkmcnt(3)
	v_fmamk_f32 v148, v160, 0x3e000000, v148
	s_waitcnt lgkmcnt(2)
	v_fmamk_f32 v146, v161, 0x3e000000, v146
	v_max3_f32 v153, v134, v148, v146
	s_waitcnt lgkmcnt(1)
	v_fmamk_f32 v136, v162, 0x3e000000, v144
	s_waitcnt lgkmcnt(0)
	v_fmamk_f32 v134, v163, 0x3e000000, v142
	v_lshl_add_u32 v144, s15, 13, v189
	v_max3_f32 v142, v153, v136, v134
	v_add_u32_e32 v153, v144, v213
	ds_read_b128 v[236:239], v153
	v_add_u32_e32 v144, v144, v211
	ds_read_b128 v[240:243], v144
	s_waitcnt lgkmcnt(1)
	v_mfma_f32_16x16x32_bf16 v[160:163], v[236:239], v[76:79], 0
	ds_read_b128 v[236:239], v153 offset:512
	s_waitcnt lgkmcnt(1)
	v_mfma_f32_16x16x32_bf16 v[160:163], v[240:243], v[72:75], v[160:163]
	ds_read_b128 v[240:243], v144 offset:512
	s_nop 7
	v_fmac_f32_e32 v141, 0x3e000000, v160
	v_fmac_f32_e32 v139, 0x3e000000, v161
	v_fmac_f32_e32 v137, 0x3e000000, v162
	v_fmac_f32_e32 v135, 0x3e000000, v163
	s_waitcnt lgkmcnt(1)
	v_mfma_f32_16x16x32_bf16 v[160:163], v[236:239], v[76:79], 0
	v_lshl_add_u32 v144, s14, 13, v189
	v_add_u32_e32 v215, v144, v213
	v_add_u32_e32 v216, v144, v211
	ds_read_b128 v[236:239], v216
	s_waitcnt lgkmcnt(1)
	v_mfma_f32_16x16x32_bf16 v[160:163], v[240:243], v[72:75], v[160:163]
	ds_read_b128 v[240:243], v215
	ds_read2_b32 v[152:153], v152 offset0:147 offset1:178
	v_max3_f32 v142, v142, v141, v139
	v_max3_f32 v142, v142, v137, v135
	s_nop 3
	v_fmac_f32_e32 v149, 0x3e000000, v160
	v_fmac_f32_e32 v147, 0x3e000000, v161
	v_fmac_f32_e32 v145, 0x3e000000, v162
	v_fmac_f32_e32 v143, 0x3e000000, v163
	s_waitcnt lgkmcnt(1)
	v_mfma_f32_16x16x32_bf16 v[160:163], v[240:243], v[76:79], 0
	ds_read_b128 v[240:243], v215 offset:512
	v_max3_f32 v142, v142, v149, v147
	v_max3_f32 v142, v142, v145, v143
	v_mfma_f32_16x16x32_bf16 v[168:171], v[236:239], v[72:75], v[160:163]
	ds_read_b128 v[236:239], v216 offset:512
	s_nop 4
	ds_read2_b32 v[162:163], v150 offset0:147 offset1:178
	ds_read2_b32 v[160:161], v151 offset0:147 offset1:178
	ds_read2_b32 v[150:151], v164 offset0:147 offset1:178
	s_waitcnt lgkmcnt(5)
	v_fmamk_f32 v144, v170, 0x3e000000, v152
	v_lshl_add_u32 v152, s6, 13, v189
	s_waitcnt lgkmcnt(2)
	v_fmamk_f32 v162, v168, 0x3e000000, v162
	s_waitcnt lgkmcnt(1)
	v_fmamk_f32 v160, v169, 0x3e000000, v160
	v_max3_f32 v168, v142, v162, v160
	s_waitcnt lgkmcnt(0)
; template <bool UPFRONT, class KP, class VP, class MOD>
; __device__ __forceinline__ void attn16(const bf16x8 (&qf)[2], KP kptr, VP vptr, MOD mod, bf16_t* outp  , int fr, int fq) {
;     ...
;         for (int r = 0; r < 4; ++r) { const float v = mod(acc[r], t >> 1, t & 1, r); acc[r] = v; mx = fmaxf(mx, v); }
;         st[t] = acc;
;     }
;     __builtin_amdgcn_sched_barrier(0);
;     bf16x8 vf[8][4];
; #pragma unroll
;     for (int s = 0; s < 8; ++s)
; #pragma unroll
;         for (int dt = 0; dt < 4; ++dt) if (UPFRONT) vf[s][dt] = vptr(16 * dt + fr, s);
;     mx = fmaxf(mx, __shfl_xor(mx, 16)); mx = fmaxf(mx, __shfl_xor(mx, 32));
;     float sum = 0.f;
; #pragma unroll
;     for (int t = 0; t < 16; ++t)
; #pragma unroll
;         for (int r = 0; r < 4; ++r) { const float e = __expf(st[t][r] - mx); st[t][r] = e; sum += e; }
	v_fmamk_f32 v142, v171, 0x3e000000, v150
	v_max3_f32 v150, v168, v144, v142
	v_mfma_f32_16x16x32_bf16 v[168:171], v[240:243], v[76:79], 0
	ds_read2_b32 v[164:165], v165 offset0:147 offset1:178
	v_mfma_f32_16x16x32_bf16 v[216:219], v[236:239], v[72:75], v[168:171]
	s_nop 4
	ds_read2_b32 v[170:171], v166 offset0:147 offset1:178
	ds_read2_b32 v[168:169], v167 offset0:147 offset1:178
	s_waitcnt lgkmcnt(2)
	v_fmamk_f32 v220, v216, 0x3e000000, v164
	v_add_u32_e32 v164, v152, v213
	ds_read_b128 v[240:243], v164
	ds_read2_b32 v[166:167], v214 offset0:147 offset1:178
	s_waitcnt lgkmcnt(3)
	v_fmamk_f32 v224, v217, 0x3e000000, v170
	v_add_u32_e32 v152, v152, v211
	ds_read_b128 v[236:239], v152
	s_waitcnt lgkmcnt(2)
	v_mfma_f32_16x16x32_bf16 v[214:217], v[240:243], v[76:79], 0
	ds_read_b128 v[240:243], v164 offset:512
	v_max3_f32 v150, v150, v220, v224
	v_fmamk_f32 v223, v218, 0x3e000000, v168
	s_waitcnt lgkmcnt(2)
	v_fmamk_f32 v221, v219, 0x3e000000, v166
	s_waitcnt lgkmcnt(1)
	v_mfma_f32_16x16x32_bf16 v[214:217], v[236:239], v[72:75], v[214:217]
	ds_read_b128 v[236:239], v152 offset:512
	v_max3_f32 v150, v150, v223, v221
	s_nop 6
	v_fmac_f32_e32 v163, 0x3e000000, v214
	v_fmac_f32_e32 v161, 0x3e000000, v215
	v_fmac_f32_e32 v153, 0x3e000000, v216
	v_fmac_f32_e32 v151, 0x3e000000, v217
	s_waitcnt lgkmcnt(1)
	v_mfma_f32_16x16x32_bf16 v[76:79], v[240:243], v[76:79], 0
	v_max3_f32 v150, v150, v163, v161
	v_max3_f32 v150, v150, v153, v151
	s_waitcnt lgkmcnt(0)
	v_mfma_f32_16x16x32_bf16 v[72:75], v[236:239], v[72:75], v[76:79]
	s_nop 7
	v_fmac_f32_e32 v165, 0x3e000000, v72
	v_fmac_f32_e32 v171, 0x3e000000, v73
	v_fmac_f32_e32 v169, 0x3e000000, v74
	v_fmac_f32_e32 v167, 0x3e000000, v75
	v_max3_f32 v72, v150, v165, v171
	v_max3_f32 v72, v72, v169, v167
	ds_bpermute_b32 v73, v199, v72
	s_lshl_b32 s0, s34, 7
	s_waitcnt lgkmcnt(0)
	v_max_f32_e32 v73, v73, v73
	v_max_f32_e32 v72, v72, v73
	ds_bpermute_b32 v73, v200, v72
	s_waitcnt lgkmcnt(0)
	v_max_f32_e32 v73, v73, v73
	v_max_f32_e32 v73, v72, v73
	v_mul_f32_e32 v235, 0xbfb8aa3b, v73
	v_fmamk_f32 v77, v99, 0x3fb8aa3b, v235
	v_exp_f32_e32 v230, v77
	v_fmamk_f32 v77, v212, 0x3fb8aa3b, v235
	v_exp_f32_e32 v231, v77
	v_fmamk_f32 v77, v112, 0x3fb8aa3b, v235
	v_exp_f32_e32 v232, v77
	v_fmamk_f32 v77, v114, 0x3fb8aa3b, v235
	v_exp_f32_e32 v233, v77
	v_fmamk_f32 v77, v102, 0x3fb8aa3b, v235
	v_exp_f32_e32 v234, v77
	v_fmamk_f32 v77, v109, 0x3fb8aa3b, v235
	v_exp_f32_e32 v212, v77
	v_fmamk_f32 v77, v107, 0x3fb8aa3b, v235
	v_exp_f32_e32 v214, v77
	v_fmamk_f32 v77, v105, 0x3fb8aa3b, v235
	v_exp_f32_e32 v217, v77
	v_fmamk_f32 v77, v103, 0x3fb8aa3b, v235
	v_exp_f32_e32 v222, v77
	v_fmamk_f32 v77, v115, 0x3fb8aa3b, v235
	v_exp_f32_e32 v225, v77
	v_fmamk_f32 v77, v113, 0x3fb8aa3b, v235
	v_exp_f32_e32 v227, v77
	v_fmamk_f32 v77, v117, 0x3fb8aa3b, v235
	v_exp_f32_e32 v228, v77
	v_fmamk_f32 v77, v111, 0x3fb8aa3b, v235
	v_exp_f32_e32 v229, v77
	v_fmamk_f32 v77, v124, 0x3fb8aa3b, v235
	v_exp_f32_e32 v150, v77
	v_fmamk_f32 v77, v122, 0x3fb8aa3b, v235
	v_exp_f32_e32 v164, v77
	v_fmamk_f32 v77, v116, 0x3fb8aa3b, v235
	v_exp_f32_e32 v168, v77
	v_fmamk_f32 v77, v110, 0x3fb8aa3b, v235
	v_exp_f32_e32 v213, v77
	v_fmamk_f32 v77, v120, 0x3fb8aa3b, v235
	v_exp_f32_e32 v215, v77
	v_fmamk_f32 v77, v128, 0x3fb8aa3b, v235
	v_exp_f32_e32 v218, v77
	v_fmamk_f32 v77, v130, 0x3fb8aa3b, v235
	v_exp_f32_e32 v219, v77
	v_fmamk_f32 v77, v118, 0x3fb8aa3b, v235
	v_exp_f32_e32 v226, v77
	v_fmamk_f32 v77, v125, 0x3fb8aa3b, v235
	v_exp_f32_e32 v125, v77
	v_fmamk_f32 v77, v123, 0x3fb8aa3b, v235
	v_exp_f32_e32 v128, v77
	v_fmamk_f32 v77, v121, 0x3fb8aa3b, v235
	v_exp_f32_e32 v130, v77
	v_fmamk_f32 v77, v119, 0x3fb8aa3b, v235
	v_exp_f32_e32 v152, v77
	v_fmamk_f32 v77, v131, 0x3fb8aa3b, v235
	v_fmamk_f32 v72, v108, 0x3fb8aa3b, v235
	v_fmamk_f32 v74, v106, 0x3fb8aa3b, v235
	v_exp_f32_e32 v166, v77
	v_fmamk_f32 v77, v129, 0x3fb8aa3b, v235
	v_exp_f32_e32 v72, v72
	v_exp_f32_e32 v74, v74
	v_exp_f32_e32 v170, v77
	v_fmamk_f32 v77, v133, 0x3fb8aa3b, v235
	v_exp_f32_e32 v211, v77
	v_fmamk_f32 v77, v127, 0x3fb8aa3b, v235
	v_add_f32_e32 v75, 0, v72
	v_add_f32_e32 v76, v74, v75
	v_fmamk_f32 v75, v104, 0x3fb8aa3b, v235
	v_exp_f32_e32 v216, v77
	v_fmamk_f32 v77, v140, 0x3fb8aa3b, v235
	v_exp_f32_e32 v75, v75
	v_exp_f32_e32 v118, v77
	v_fmamk_f32 v77, v138, 0x3fb8aa3b, v235
	v_exp_f32_e32 v120, v77
	v_fmamk_f32 v77, v132, 0x3fb8aa3b, v235
	v_add_f32_e32 v76, v75, v76
	v_exp_f32_e32 v122, v77
	v_fmamk_f32 v77, v126, 0x3fb8aa3b, v235
	v_add_f32_e32 v76, v230, v76
	v_add_f32_e32 v76, v231, v76
	v_exp_f32_e32 v126, v77
	v_fmamk_f32 v77, v148, 0x3fb8aa3b, v235
	v_add_f32_e32 v76, v232, v76
	v_add_f32_e32 v76, v233, v76
	v_exp_f32_e32 v127, v77
	v_fmamk_f32 v77, v146, 0x3fb8aa3b, v235
	v_add_f32_e32 v76, v234, v76
	v_add_f32_e32 v76, v212, v76
	v_exp_f32_e32 v131, v77
	v_fmamk_f32 v77, v136, 0x3fb8aa3b, v235
	v_add_f32_e32 v76, v214, v76
	v_add_f32_e32 v76, v217, v76
	v_exp_f32_e32 v132, v77
	v_fmamk_f32 v77, v134, 0x3fb8aa3b, v235
	v_add_f32_e32 v76, v222, v76
	v_add_f32_e32 v76, v225, v76
	v_exp_f32_e32 v133, v77
	v_fmamk_f32 v77, v141, 0x3fb8aa3b, v235
	v_add_f32_e32 v76, v227, v76
	v_add_f32_e32 v76, v228, v76
	v_exp_f32_e32 v110, v77
	v_fmamk_f32 v77, v139, 0x3fb8aa3b, v235
	v_add_f32_e32 v76, v229, v76
	v_add_f32_e32 v76, v150, v76
	v_exp_f32_e32 v113, v77
	v_fmamk_f32 v77, v137, 0x3fb8aa3b, v235
	v_add_f32_e32 v76, v164, v76
	v_add_f32_e32 v76, v168, v76
	v_exp_f32_e32 v116, v77
	v_fmamk_f32 v77, v135, 0x3fb8aa3b, v235
	v_add_f32_e32 v76, v213, v76
	v_add_f32_e32 v76, v215, v76
	v_exp_f32_e32 v119, v77
	v_fmamk_f32 v77, v149, 0x3fb8aa3b, v235
	v_add_f32_e32 v76, v218, v76
; template <bool UPFRONT, class KP, class VP, class MOD>
; __device__ __forceinline__ void attn16(const bf16x8 (&qf)[2], KP kptr, VP vptr, MOD mod, bf16_t* outp  , int fr, int fq) {
;     ...
;     for (int t = 0; t < 16; ++t)
; #pragma unroll
;         for (int r = 0; r < 4; ++r) { const float e = __expf(st[t][r] - mx); st[t][r] = e; sum += e; }
;     sum += __shfl_xor(sum, 16); sum += __shfl_xor(sum, 32);
;     f32x4 o[4];
; #pragma unroll
;     for (int dt = 0; dt < 4; ++dt) o[dt] = (f32x4){0.f, 0.f, 0.f, 0.f};
; #pragma unroll
;     for (int s = 0; s < 8; ++s) {
;         u32x4 pw; pw.x = cvt_pk_bf16(st[2 * s][0], st[2 * s][1]); pw.y = cvt_pk_bf16(st[2 * s][2], st[2 * s][3]);
;         pw.z = cvt_pk_bf16(st[2 * s + 1][0], st[2 * s + 1][1]); pw.w = cvt_pk_bf16(st[2 * s + 1][2], st[2 * s + 1][3]);
;         bf16x8 pf; __builtin_memcpy(&pf, &pw, 16);
; #pragma unroll
;         for (int dt = 0; dt < 4; ++dt) { if (!UPFRONT) vf[s][dt] = vptr(16 * dt + fr, s); o[dt] = __builtin_amdgcn_mfma_f32_16x16x32_bf16(vf[s][dt], pf, o[dt], 0, 0, 0); }
	v_add_f32_e32 v76, v219, v76
	v_exp_f32_e32 v121, v77
	v_fmamk_f32 v77, v147, 0x3fb8aa3b, v235
	v_add_f32_e32 v76, v226, v76
	v_add_f32_e32 v76, v125, v76
	v_exp_f32_e32 v123, v77
	v_fmamk_f32 v77, v145, 0x3fb8aa3b, v235
	v_add_f32_e32 v76, v128, v76
	v_add_f32_e32 v76, v130, v76
	v_exp_f32_e32 v124, v77
	v_fmamk_f32 v77, v143, 0x3fb8aa3b, v235
	v_add_f32_e32 v76, v152, v76
	v_add_f32_e32 v76, v166, v76
	v_exp_f32_e32 v129, v77
	v_fmamk_f32 v77, v162, 0x3fb8aa3b, v235
	v_add_f32_e32 v76, v170, v76
	v_add_f32_e32 v76, v211, v76
	v_exp_f32_e32 v107, v77
	v_fmamk_f32 v77, v160, 0x3fb8aa3b, v235
	v_add_f32_e32 v76, v216, v76
	v_add_f32_e32 v76, v118, v76
	v_exp_f32_e32 v108, v77
	v_fmamk_f32 v77, v144, 0x3fb8aa3b, v235
	v_add_f32_e32 v76, v120, v76
	v_add_f32_e32 v76, v122, v76
	v_exp_f32_e32 v109, v77
	v_fmamk_f32 v77, v142, 0x3fb8aa3b, v235
	v_add_f32_e32 v76, v126, v76
	v_add_f32_e32 v76, v127, v76
	v_exp_f32_e32 v111, v77
	v_fmamk_f32 v77, v220, 0x3fb8aa3b, v235
	v_add_f32_e32 v76, v131, v76
	v_add_f32_e32 v76, v132, v76
	v_exp_f32_e32 v112, v77
	v_fmamk_f32 v77, v224, 0x3fb8aa3b, v235
	v_add_f32_e32 v76, v133, v76
	v_add_f32_e32 v76, v110, v76
	v_exp_f32_e32 v114, v77
	v_fmamk_f32 v77, v223, 0x3fb8aa3b, v235
	v_add_f32_e32 v76, v113, v76
	v_add_f32_e32 v76, v116, v76
	v_exp_f32_e32 v115, v77
	v_fmamk_f32 v77, v221, 0x3fb8aa3b, v235
	v_add_f32_e32 v76, v119, v76
	v_add_f32_e32 v76, v121, v76
	v_exp_f32_e32 v117, v77
	v_fmamk_f32 v77, v163, 0x3fb8aa3b, v235
	v_add_f32_e32 v76, v123, v76
	v_add_f32_e32 v76, v124, v76
	v_exp_f32_e32 v78, v77
	v_fmamk_f32 v77, v161, 0x3fb8aa3b, v235
	v_add_f32_e32 v76, v129, v76
	v_add_f32_e32 v76, v107, v76
	v_exp_f32_e32 v79, v77
	v_fmamk_f32 v77, v153, 0x3fb8aa3b, v235
	v_add_f32_e32 v76, v108, v76
	v_add_f32_e32 v76, v109, v76
	v_exp_f32_e32 v99, v77
	v_fmamk_f32 v77, v151, 0x3fb8aa3b, v235
	v_add_f32_e32 v76, v111, v76
	v_add_f32_e32 v76, v112, v76
	v_exp_f32_e32 v102, v77
	v_fmamk_f32 v77, v165, 0x3fb8aa3b, v235
	v_add_f32_e32 v76, v114, v76
	v_add_f32_e32 v76, v115, v76
	v_exp_f32_e32 v103, v77
	v_fmamk_f32 v77, v171, 0x3fb8aa3b, v235
	v_add_f32_e32 v76, v117, v76
	v_add_f32_e32 v76, v78, v76
	v_exp_f32_e32 v104, v77
	v_fmamk_f32 v77, v169, 0x3fb8aa3b, v235
	v_add_f32_e32 v76, v79, v76
	v_fmamk_f32 v73, v167, 0x3fb8aa3b, v235
	v_add_f32_e32 v76, v99, v76
	v_exp_f32_e32 v105, v77
	v_add_f32_e32 v76, v102, v76
	v_exp_f32_e32 v106, v73
	v_add_f32_e32 v76, v103, v76
	v_add3_u32 v146, v210, s0, v190
	ds_read_b128 v[240:243], v146
	ds_read_b128 v[236:239], v146 offset:37888
	v_add_f32_e32 v76, v104, v76
	v_add_f32_e32 v76, v105, v76
	v_add_f32_e32 v73, v106, v76
	s_lshl_b32 s0, s31, 7
	ds_bpermute_b32 v76, v199, v73
	ds_read_b128 v[138:141], v146 offset:18944
	ds_read_b128 v[146:149], v146 offset:56832
	v_add3_u32 v151, v210, s0, v190
	ds_read_b128 v[160:163], v151
	s_waitcnt lgkmcnt(3)
	v_add_f32_e32 v76, v73, v76
	v_cvt_pk_bf16_f32 v72, v72, v74
	v_cvt_pk_bf16_f32 v73, v75, v230
	v_cvt_pk_bf16_f32 v74, v231, v232
	v_cvt_pk_bf16_f32 v75, v233, v234
	s_lshl_b32 s0, s30, 7
	v_cvt_pk_bf16_f32 v119, v116, v119
	v_mfma_f32_16x16x32_bf16 v[134:137], v[240:243], v[72:75], 0
	ds_read_b128 v[240:243], v151 offset:18944
	v_cvt_pk_bf16_f32 v108, v107, v108
	v_cvt_pk_bf16_f32 v109, v109, v111
	v_cvt_pk_bf16_f32 v111, v115, v117
	s_waitcnt lgkmcnt(3)
	v_mfma_f32_16x16x32_bf16 v[138:141], v[138:141], v[72:75], 0
	ds_bpermute_b32 v77, v200, v76
	s_waitcnt lgkmcnt(0)
	v_add_f32_e32 v76, v76, v77
	v_mfma_f32_16x16x32_bf16 v[142:145], v[236:239], v[72:75], 0
	ds_read_b128 v[236:239], v151 offset:37888
	v_mfma_f32_16x16x32_bf16 v[72:75], v[146:149], v[72:75], 0
	v_cvt_pk_bf16_f32 v146, v212, v214
	v_cvt_pk_bf16_f32 v147, v217, v222
	v_cvt_pk_bf16_f32 v148, v225, v227
	v_cvt_pk_bf16_f32 v149, v228, v229
	s_nop 1
	v_mfma_f32_16x16x32_bf16 v[134:137], v[160:163], v[146:149], v[134:137]
	v_mfma_f32_16x16x32_bf16 v[138:141], v[240:243], v[146:149], v[138:141]
	ds_read_b128 v[240:243], v151 offset:56832
	s_waitcnt lgkmcnt(1)
	v_mfma_f32_16x16x32_bf16 v[142:145], v[236:239], v[146:149], v[142:145]
	s_waitcnt lgkmcnt(0)
	v_mfma_f32_16x16x32_bf16 v[72:75], v[240:243], v[146:149], v[72:75]
	v_cvt_pk_bf16_f32 v146, v150, v164
	v_add3_u32 v150, v210, s0, v190
	ds_read_b128 v[236:239], v150
	ds_read_b128 v[240:243], v150 offset:18944
	v_cvt_pk_bf16_f32 v147, v168, v213
	v_cvt_pk_bf16_f32 v148, v215, v218
	v_cvt_pk_bf16_f32 v149, v219, v226
	s_lshl_b32 s0, s29, 7
	s_waitcnt lgkmcnt(1)
	v_mfma_f32_16x16x32_bf16 v[134:137], v[236:239], v[146:149], v[134:137]
	ds_read_b128 v[236:239], v150 offset:37888
	s_waitcnt lgkmcnt(1)
	v_mfma_f32_16x16x32_bf16 v[138:141], v[240:243], v[146:149], v[138:141]
	ds_read_b128 v[240:243], v150 offset:56832
	s_waitcnt lgkmcnt(1)
	v_mfma_f32_16x16x32_bf16 v[142:145], v[236:239], v[146:149], v[142:145]
	s_waitcnt lgkmcnt(0)
; template <bool UPFRONT, class KP, class VP, class MOD>
; __device__ __forceinline__ void attn16(const bf16x8 (&qf)[2], KP kptr, VP vptr, MOD mod, bf16_t* outp  , int fr, int fq) {
;     ...
;     for (int s = 0; s < 8; ++s) {
;         u32x4 pw; pw.x = cvt_pk_bf16(st[2 * s][0], st[2 * s][1]); pw.y = cvt_pk_bf16(st[2 * s][2], st[2 * s][3]);
;         pw.z = cvt_pk_bf16(st[2 * s + 1][0], st[2 * s + 1][1]); pw.w = cvt_pk_bf16(st[2 * s + 1][2], st[2 * s + 1][3]);
;         bf16x8 pf; __builtin_memcpy(&pf, &pw, 16);
; #pragma unroll
;         for (int dt = 0; dt < 4; ++dt) { if (!UPFRONT) vf[s][dt] = vptr(16 * dt + fr, s); o[dt] = __builtin_amdgcn_mfma_f32_16x16x32_bf16(vf[s][dt], pf, o[dt], 0, 0, 0); }
;     }
;     const float inv = 1.0f / sum;
; #pragma unroll
;     for (int dt = 0; dt < 4; ++dt) { u32x2 w; w.x = cvt_pk_bf16(o[dt][0] * inv, o[dt][1] * inv); w.y = cvt_pk_bf16(o[dt][2] * inv, o[dt][3] * inv);
;         *(u32x2*)(outp + 16 * dt + 4 * fq) = w; }
	v_mfma_f32_16x16x32_bf16 v[72:75], v[240:243], v[146:149], v[72:75]
	v_cvt_pk_bf16_f32 v146, v125, v128
	v_add3_u32 v125, v210, s0, v190
	ds_read_b128 v[236:239], v125
	ds_read_b128 v[240:243], v125 offset:18944
	v_cvt_pk_bf16_f32 v147, v130, v152
	v_cvt_pk_bf16_f32 v148, v166, v170
	v_cvt_pk_bf16_f32 v149, v211, v216
	s_lshl_b32 s0, s28, 7
	s_waitcnt lgkmcnt(1)
	v_mfma_f32_16x16x32_bf16 v[134:137], v[236:239], v[146:149], v[134:137]
	ds_read_b128 v[236:239], v125 offset:37888
	s_waitcnt lgkmcnt(1)
	v_mfma_f32_16x16x32_bf16 v[138:141], v[240:243], v[146:149], v[138:141]
	ds_read_b128 v[240:243], v125 offset:56832
	s_waitcnt lgkmcnt(1)
	v_mfma_f32_16x16x32_bf16 v[142:145], v[236:239], v[146:149], v[142:145]
	s_waitcnt lgkmcnt(0)
	v_mfma_f32_16x16x32_bf16 v[72:75], v[240:243], v[146:149], v[72:75]
	v_cvt_pk_bf16_f32 v146, v118, v120
	v_add3_u32 v118, v210, s0, v190
	ds_read_b128 v[236:239], v118
	ds_read_b128 v[240:243], v118 offset:18944
	v_cvt_pk_bf16_f32 v148, v127, v131
	v_cvt_pk_bf16_f32 v149, v132, v133
	v_cvt_pk_bf16_f32 v147, v122, v126
	s_lshl_b32 s0, s15, 7
	v_cvt_pk_bf16_f32 v120, v121, v123
	s_waitcnt lgkmcnt(1)
	v_mfma_f32_16x16x32_bf16 v[130:133], v[236:239], v[146:149], v[134:137]
	ds_read_b128 v[236:239], v118 offset:37888
	s_nop 2
	v_cvt_pk_bf16_f32 v121, v124, v129
	s_waitcnt lgkmcnt(1)
	v_mfma_f32_16x16x32_bf16 v[134:137], v[240:243], v[146:149], v[138:141]
	ds_read_b128 v[240:243], v118 offset:56832
	s_nop 2
	s_waitcnt lgkmcnt(1)
	v_mfma_f32_16x16x32_bf16 v[138:141], v[236:239], v[146:149], v[142:145]
	s_nop 2
	v_cvt_pk_bf16_f32 v118, v110, v113
	v_add3_u32 v110, v210, s0, v190
	ds_read_b128 v[236:239], v110
	ds_read_b128 v[126:129], v110 offset:18944
	s_waitcnt lgkmcnt(1)
	v_mfma_f32_16x16x32_bf16 v[122:125], v[236:239], v[118:121], v[130:133]
	ds_read_b128 v[236:239], v110 offset:37888
	s_nop 2
	s_lshl_b32 s0, s14, 7
	v_add3_u32 v107, v210, s0, v190
	s_waitcnt lgkmcnt(1)
	v_mfma_f32_16x16x32_bf16 v[126:129], v[126:129], v[118:121], v[134:137]
	s_lshl_b32 s0, s6, 7
	s_nop 1
	ds_read_b128 v[134:137], v110 offset:56832
	v_mfma_f32_16x16x32_bf16 v[72:75], v[240:243], v[146:149], v[72:75]
	ds_read_b128 v[240:243], v107
	v_cvt_pk_bf16_f32 v110, v112, v114
	s_waitcnt lgkmcnt(2)
	v_mfma_f32_16x16x32_bf16 v[130:133], v[236:239], v[118:121], v[138:141]
	ds_read_b128 v[236:239], v107 offset:18944
	s_waitcnt lgkmcnt(2)
	v_mfma_f32_16x16x32_bf16 v[72:75], v[134:137], v[118:121], v[72:75]
	s_waitcnt lgkmcnt(1)
	v_mfma_f32_16x16x32_bf16 v[112:115], v[240:243], v[108:111], v[122:125]
	ds_read_b128 v[240:243], v107 offset:37888
	s_waitcnt lgkmcnt(1)
	v_mfma_f32_16x16x32_bf16 v[116:119], v[236:239], v[108:111], v[126:129]
	ds_read_b128 v[236:239], v107 offset:56832
	s_nop 0
	s_nop 0
	s_waitcnt lgkmcnt(1)
	v_mfma_f32_16x16x32_bf16 v[120:123], v[240:243], v[108:111], v[130:133]
	s_waitcnt lgkmcnt(0)
	v_mfma_f32_16x16x32_bf16 v[72:75], v[236:239], v[108:111], v[72:75]
	v_cvt_pk_bf16_f32 v108, v78, v79
	v_add3_u32 v78, v210, s0, v190
	ds_read_b128 v[240:243], v78
	ds_read_b128 v[236:239], v78 offset:18944
	v_cvt_pk_bf16_f32 v109, v99, v102
	v_cvt_pk_bf16_f32 v110, v103, v104
	v_cvt_pk_bf16_f32 v111, v105, v106
	v_div_scale_f32 v77, s[0:1], v76, v76, 1.0
	s_waitcnt lgkmcnt(1)
	v_mfma_f32_16x16x32_bf16 v[102:105], v[240:243], v[108:111], v[112:115]
	ds_read_b128 v[240:243], v78 offset:37888
	s_nop 2
	s_waitcnt lgkmcnt(1)
	v_mfma_f32_16x16x32_bf16 v[112:115], v[236:239], v[108:111], v[116:119]
	ds_read_b128 v[236:239], v78 offset:56832
	s_nop 2
	s_waitcnt lgkmcnt(1)
	v_mfma_f32_16x16x32_bf16 v[116:119], v[240:243], v[108:111], v[120:123]
	s_nop 2
	v_rcp_f32_e32 v78, v77
	s_waitcnt lgkmcnt(0)
	v_mfma_f32_16x16x32_bf16 v[72:75], v[236:239], v[108:111], v[72:75]
	v_fma_f32 v79, -v77, v78, 1.0
	v_fmac_f32_e32 v78, v79, v78
	v_div_scale_f32 v79, vcc, 1.0, v76, 1.0
	v_mul_f32_e32 v99, v79, v78
	v_fma_f32 v106, -v77, v99, v79
	v_fmac_f32_e32 v99, v106, v78
	v_fma_f32 v77, -v77, v99, v79
	v_div_fmas_f32 v77, v77, v78, v99
	v_div_fixup_f32 v99, v77, v76, 1.0
	v_mul_f32_e32 v78, v102, v99
	v_mul_f32_e32 v79, v103, v99
	v_lshl_add_u64 v[76:77], v[94:95], 0, v[100:101]
	v_cvt_pk_bf16_f32 v78, v78, v79
	v_mul_f32_e32 v79, v104, v99
	v_mul_f32_e32 v100, v105, v99
	v_cvt_pk_bf16_f32 v79, v79, v100
	global_store_dwordx2 v[76:77], v[78:79], off
	v_mul_f32_e32 v78, v112, v99
	v_mul_f32_e32 v79, v113, v99
	v_cvt_pk_bf16_f32 v78, v78, v79
	v_mul_f32_e32 v79, v114, v99
	v_mul_f32_e32 v100, v115, v99
	v_cvt_pk_bf16_f32 v79, v79, v100
	global_store_dwordx2 v[76:77], v[78:79], off offset:32
	v_mul_f32_e32 v78, v116, v99
	v_mul_f32_e32 v79, v117, v99
	v_mul_f32_e32 v72, v72, v99
	v_mul_f32_e32 v73, v73, v99
	v_cvt_pk_bf16_f32 v78, v78, v79
	v_mul_f32_e32 v79, v118, v99
	v_mul_f32_e32 v100, v119, v99
	v_cvt_pk_bf16_f32 v72, v72, v73
	v_mul_f32_e32 v73, v74, v99
	v_mul_f32_e32 v74, v75, v99
	v_cvt_pk_bf16_f32 v79, v79, v100
	v_cvt_pk_bf16_f32 v73, v73, v74
	global_store_dwordx2 v[76:77], v[78:79], off offset:64
	global_store_dwordx2 v[76:77], v[72:73], off offset:96
	s_add_i32 s74, s74, 2
	s_add_i32 s52, s52, -2
	s_cmp_eq_u32 s74, 8
	v_add_u32_e32 v98, 0x80, v98
	s_cbranch_scc1 .LBB0_126
	s_mov_b32 s0, s75
	s_branch .LBB0_128
